# EpiResid (down/out epilogues): counted vmcnt waits per row group instead of draining all 16 residual loads first
# baseline (speedup 1.0000x reference)
; __device__ __forceinline__ unsigned cvt_pk_bf16(float lo, float hi) { f32x2_t v = {lo, hi}; bf16x2_t b = __builtin_convertvector(v, bf16x2_t); return __builtin_bit_cast(unsigned, b); }
; #define wt16(p, v) wt16b(WSB, (p), (v))
;     __device__ __forceinline__ void operator()(const f32x4 (&acc)[2][2][4][2], const pg8::Unit& u, int wr, int wc, int fr, int fq) const {
;         const int row0 = u.pm * 256 + wr * 64 + fr, col0 = u.pn * 256 + wc * 32 + 8 * fq;
;         f32x4 pre[4][2][2];
; #pragma unroll
;         for (int m = 0; m < 4; ++m)
; #pragma unroll
;             for (int bj = 0; bj < 2; ++bj) { const size_t off = (size_t)(row0 + m * 16) * DM + col0 + bj * 128;
;                 pre[m][bj][0] = *(const f32x4*)(base + off); pre[m][bj][1] = *(const f32x4*)(base + off + 4); }
; #pragma unroll
;         for (int ai = 0; ai < 2; ++ai)
; #pragma unroll
;             for (int m = 0; m < 4; ++m) {
;                 const int row = row0 + ai * 128 + m * 16; float part = 0.f;
;                 f32x4 v[2][2];
; #pragma unroll
;                 for (int bj = 0; bj < 2; ++bj) { v[bj][0] = pre[m][bj][0] + acc[ai][bj][m][0] * scale; v[bj][1] = pre[m][bj][1] + acc[ai][bj][m][1] * scale; }
;                 if (ai == 0) {
; #pragma unroll
;                     for (int bj = 0; bj < 2; ++bj) { const size_t off2 = (size_t)(row + 128) * DM + col0 + bj * 128;
;                         pre[m][bj][0] = *(const f32x4*)(base + off2); pre[m][bj][1] = *(const f32x4*)(base + off2 + 4); }
;                 }
; #pragma unroll
;                 for (int bj = 0; bj < 2; ++bj) {
;                     const size_t off = (size_t)row * DM + col0 + bj * 128;
;                     const f32x4 v0 = v[bj][0], v1 = v[bj][1];
;                     *(f32x4*)(out + off) = v0; *(f32x4*)(out + off + 4) = v1;
;                     u32x4 w; w.x = cvt_pk_bf16(v0[0], v0[1]); w.y = cvt_pk_bf16(v0[2], v0[3]); w.z = cvt_pk_bf16(v1[0], v1[1]); w.w = cvt_pk_bf16(v1[2], v1[3]);
;                     wt16(xb + (size_t)row * XLD + col0 + bj * 128, w);
;                     part += (v0[0] * v0[0] + v0[1] * v0[1]) + (v0[2] * v0[2] + v0[3] * v0[3]) + (v1[0] * v1[0] + v1[1] * v1[1]) + (v1[2] * v1[2] + v1[3] * v1[3]);
;                 }
;                 part += __shfl_xor(part, 16); part += __shfl_xor(part, 32);
;                 if (fq == 0) wt4f(ss + (size_t)row * 16 + u.pn * 4 + wc, part);
.Lea_s0:
	s_nop 0
	v_lshl_or_b32 v228, s48, 8, v234
	v_lshl_add_u32 v214, s50, 8, v194
	v_ashrrev_i32_e32 v229, 31, v228
	v_lshlrev_b64 v[212:213], 2, v[228:229]
	v_ashrrev_i32_e32 v215, 31, v214
	s_waitcnt lgkmcnt(0)
	v_lshl_add_u64 v[130:131], s[16:17], 0, v[212:213]
	v_lshlrev_b64 v[232:233], 12, v[214:215]
	v_lshl_add_u64 v[132:133], v[130:131], 0, v[232:233]
	global_load_dwordx4 v[178:181], v[132:133], off offset:16
	global_load_dwordx4 v[182:185], v[132:133], off
	global_load_dwordx4 v[216:219], v[132:133], off offset:528
	global_load_dwordx4 v[236:239], v[132:133], off offset:512
	v_and_b32_e32 v187, 64, v247
	v_xor_b32_e32 v186, 16, v247
	v_add_u32_e32 v187, 64, v187
	v_cmp_lt_i32_e32 vcc, v186, v187
	v_or_b32_e32 v226, 16, v214
	v_add_u32_e32 v210, 0x80, v214
	v_cndmask_b32_e32 v186, v247, v186, vcc
	v_lshlrev_b32_e32 v197, 2, v186
	v_xor_b32_e32 v186, 32, v247
	v_cmp_lt_i32_e32 vcc, v186, v187
	v_ashrrev_i32_e32 v227, 31, v226
	v_or_b32_e32 v222, 32, v214
	v_or_b32_e32 v208, 48, v214
	v_cndmask_b32_e32 v186, v247, v186, vcc
	v_ashrrev_i32_e32 v211, 31, v210
	v_lshlrev_b64 v[230:231], 12, v[226:227]
	v_ashrrev_i32_e32 v223, 31, v222
	v_ashrrev_i32_e32 v209, 31, v208
	v_lshlrev_b32_e32 v196, 2, v186
	v_lshl_add_u64 v[132:133], v[130:131], 0, v[230:231]
	v_lshlrev_b64 v[224:225], 12, v[222:223]
	v_lshlrev_b64 v[220:221], 12, v[208:209]
	global_load_dwordx4 v[166:169], v[132:133], off offset:16
	global_load_dwordx4 v[174:177], v[132:133], off
	global_load_dwordx4 v[162:165], v[132:133], off offset:528
	global_load_dwordx4 v[170:173], v[132:133], off offset:512
	v_lshl_add_u64 v[132:133], v[130:131], 0, v[224:225]
	v_lshl_add_u64 v[138:139], v[130:131], 0, v[220:221]
	global_load_dwordx4 v[150:153], v[132:133], off offset:16
	global_load_dwordx4 v[158:161], v[132:133], off
	global_load_dwordx4 v[146:149], v[132:133], off offset:528
	global_load_dwordx4 v[154:157], v[132:133], off offset:512
	global_load_dwordx4 v[134:137], v[138:139], off offset:16
	global_load_dwordx4 v[142:145], v[138:139], off
	s_nop 0
	global_load_dwordx4 v[130:133], v[138:139], off offset:528
	s_nop 0
	global_load_dwordx4 v[138:141], v[138:139], off offset:512
	s_mov_b32 s58, s62
	s_mov_b32 s59, s63
	s_lshl_b32 s44, s48, 2
	s_ashr_i32 s45, s44, 31
	s_waitcnt vmcnt(12)
	v_pk_add_f32 v[186:187], v[126:127], v[178:179]
	v_pk_add_f32 v[188:189], v[128:129], v[180:181]
	v_pk_add_f32 v[178:179], v[114:115], v[216:217]
	v_lshlrev_b64 v[216:217], 12, v[210:211]
	v_lshl_add_u64 v[114:115], s[16:17], 0, v[216:217]
	v_pk_add_f32 v[180:181], v[116:117], v[218:219]
	v_lshl_add_u64 v[218:219], v[114:115], 0, v[212:213]
	v_pk_add_f32 v[192:193], v[124:125], v[184:185]
	v_pk_add_f32 v[190:191], v[122:123], v[182:183]
	v_pk_add_f32 v[184:185], v[120:121], v[238:239]
	v_pk_add_f32 v[182:183], v[118:119], v[236:237]
	global_load_dwordx4 v[118:121], v[218:219], off offset:16
	global_load_dwordx4 v[114:117], v[218:219], off
	global_load_dwordx4 v[126:129], v[218:219], off offset:528
	global_load_dwordx4 v[122:125], v[218:219], off offset:512
	v_lshl_add_u64 v[236:237], s[16:17], 0, v[232:233]
	v_lshl_add_u64 v[240:241], v[236:237], 0, v[212:213]
	global_store_dwordx4 v[240:241], v[190:193], off
	global_store_dwordx4 v[240:241], v[186:189], off offset:16
	v_cvt_pk_bf16_f32 v236, v190, v191
	v_mul_f32_e32 v191, v191, v191
	v_fmac_f32_e32 v191, v190, v190
	v_mul_f32_e32 v190, v193, v193
	v_cvt_pk_bf16_f32 v238, v186, v187
	v_fmac_f32_e32 v190, v192, v192
	v_mul_f32_e32 v187, v187, v187
	v_lshlrev_b32_e32 v217, 1, v228
	v_add_f32_e32 v190, v191, v190
	v_fmac_f32_e32 v187, v186, v186
	v_add3_u32 v217, s5, v232, v217
	v_add_f32_e32 v186, v190, v187
	v_mul_f32_e32 v187, v189, v189
	v_cvt_pk_bf16_f32 v237, v192, v193
	v_cvt_pk_bf16_f32 v239, v188, v189
	v_subrev_u32_e32 v217, s66, v217
	v_fmac_f32_e32 v187, v188, v188
	buffer_store_dwordx4 v[236:239], v217, s[56:59], 0 offen sc1
	v_add_f32_e32 v190, v187, v186
	global_store_dwordx4 v[240:241], v[182:185], off offset:512
	global_store_dwordx4 v[240:241], v[178:181], off offset:528
	v_cvt_pk_bf16_f32 v186, v182, v183
	v_mul_f32_e32 v183, v183, v183
	v_fmac_f32_e32 v183, v182, v182
	v_mul_f32_e32 v182, v185, v185
	v_cvt_pk_bf16_f32 v188, v178, v179
	v_fmac_f32_e32 v182, v184, v184
	v_mul_f32_e32 v179, v179, v179
	v_add_f32_e32 v182, v183, v182
	v_fmac_f32_e32 v179, v178, v178
	v_add_f32_e32 v178, v182, v179
	v_mul_f32_e32 v179, v181, v181
	v_fmac_f32_e32 v179, v180, v180
	v_add_f32_e32 v178, v179, v178
	v_add_f32_e32 v178, v190, v178
	ds_bpermute_b32 v179, v197, v178
	v_cvt_pk_bf16_f32 v187, v184, v185
	v_cvt_pk_bf16_f32 v189, v180, v181
	buffer_store_dwordx4 v[186:189], v217, s[56:59], 0 offen offset:256 sc1
	s_waitcnt lgkmcnt(0)
	v_add_f32_e32 v178, v178, v179
	ds_bpermute_b32 v179, v196, v178
	s_and_saveexec_b64 s[2:3], s[40:41]
	s_cbranch_execz .LBB0_42
	s_waitcnt lgkmcnt(0)
	v_add_f32_e32 v180, v178, v179
	v_lshlrev_b64 v[178:179], 6, v[214:215]
	v_lshl_add_u64 v[178:179], s[66:67], 0, v[178:179]
	v_lshl_add_u64 v[178:179], s[44:45], 2, v[178:179]
	s_lshl_b32 s34, s51, 2
	v_lshl_add_u64 v[178:179], v[178:179], 0, s[34:35]
	global_store_dword v[178:179], v180, off sc1
; __device__ __forceinline__ unsigned cvt_pk_bf16(float lo, float hi) { f32x2_t v = {lo, hi}; bf16x2_t b = __builtin_convertvector(v, bf16x2_t); return __builtin_bit_cast(unsigned, b); }
; #define wt16(p, v) wt16b(WSB, (p), (v))
; __device__ __forceinline__ void wt4f(float* p, float v) { __hip_atomic_store(p, v, __ATOMIC_RELAXED, __HIP_MEMORY_SCOPE_AGENT); }
;     __device__ __forceinline__ void operator()(const f32x4 (&acc)[2][2][4][2], const pg8::Unit& u, int wr, int wc, int fr, int fq) const {
;     ...
;         for (int ai = 0; ai < 2; ++ai)
; #pragma unroll
;             for (int m = 0; m < 4; ++m) {
;                 const int row = row0 + ai * 128 + m * 16; float part = 0.f;
;                 f32x4 v[2][2];
; #pragma unroll
;                 for (int bj = 0; bj < 2; ++bj) { v[bj][0] = pre[m][bj][0] + acc[ai][bj][m][0] * scale; v[bj][1] = pre[m][bj][1] + acc[ai][bj][m][1] * scale; }
;                 if (ai == 0) {
; #pragma unroll
;                     for (int bj = 0; bj < 2; ++bj) { const size_t off2 = (size_t)(row + 128) * DM + col0 + bj * 128;
;                         pre[m][bj][0] = *(const f32x4*)(base + off2); pre[m][bj][1] = *(const f32x4*)(base + off2 + 4); }
;                 }
; #pragma unroll
;                 for (int bj = 0; bj < 2; ++bj) {
;                     const size_t off = (size_t)row * DM + col0 + bj * 128;
;                     const f32x4 v0 = v[bj][0], v1 = v[bj][1];
;                     *(f32x4*)(out + off) = v0; *(f32x4*)(out + off + 4) = v1;
;                     u32x4 w; w.x = cvt_pk_bf16(v0[0], v0[1]); w.y = cvt_pk_bf16(v0[2], v0[3]); w.z = cvt_pk_bf16(v1[0], v1[1]); w.w = cvt_pk_bf16(v1[2], v1[3]);
;                     wt16(xb + (size_t)row * XLD + col0 + bj * 128, w);
;                     part += (v0[0] * v0[0] + v0[1] * v0[1]) + (v0[2] * v0[2] + v0[3] * v0[3]) + (v1[0] * v1[0] + v1[1] * v1[1]) + (v1[2] * v1[2] + v1[3] * v1[3]);
;                 }
;                 part += __shfl_xor(part, 16); part += __shfl_xor(part, 32);
;                 if (fq == 0) wt4f(ss + (size_t)row * 16 + u.pn * 4 + wc, part);
.LBB0_42:
	s_or_b64 exec, exec, s[2:3]
	s_waitcnt vmcnt(18)
	s_nop 0
	v_pk_add_f32 v[182:183], v[98:99], v[162:163]
	v_add_u32_e32 v162, 0x90, v214
	v_ashrrev_i32_e32 v163, 31, v162
	s_waitcnt lgkmcnt(0)
	v_pk_add_f32 v[178:179], v[106:107], v[166:167]
	v_lshlrev_b64 v[166:167], 12, v[162:163]
	v_lshl_add_u64 v[98:99], s[16:17], 0, v[166:167]
	v_pk_add_f32 v[184:185], v[100:101], v[164:165]
	v_lshl_add_u64 v[164:165], v[98:99], 0, v[212:213]
	v_pk_add_f32 v[176:177], v[112:113], v[176:177]
	v_pk_add_f32 v[174:175], v[110:111], v[174:175]
	v_pk_add_f32 v[180:181], v[108:109], v[168:169]
	v_pk_add_f32 v[172:173], v[104:105], v[172:173]
	v_pk_add_f32 v[170:171], v[102:103], v[170:171]
	global_load_dwordx4 v[102:105], v[164:165], off offset:16
	global_load_dwordx4 v[98:101], v[164:165], off
	global_load_dwordx4 v[110:113], v[164:165], off offset:528
	global_load_dwordx4 v[106:109], v[164:165], off offset:512
	v_lshl_add_u64 v[168:169], s[16:17], 0, v[230:231]
	v_lshlrev_b32_e32 v167, 1, v228
	v_lshl_add_u64 v[168:169], v[168:169], 0, v[212:213]
	v_add3_u32 v190, s5, v230, v167
	global_store_dwordx4 v[168:169], v[174:177], off
	global_store_dwordx4 v[168:169], v[178:181], off offset:16
	v_cvt_pk_bf16_f32 v186, v174, v175
	v_cvt_pk_bf16_f32 v187, v176, v177
	v_cvt_pk_bf16_f32 v188, v178, v179
	v_cvt_pk_bf16_f32 v189, v180, v181
	v_subrev_u32_e32 v190, s66, v190
	v_mul_f32_e32 v175, v175, v175
	buffer_store_dwordx4 v[186:189], v190, s[56:59], 0 offen sc1
	v_fmac_f32_e32 v175, v174, v174
	v_mul_f32_e32 v174, v177, v177
	global_store_dwordx4 v[168:169], v[170:173], off offset:512
	global_store_dwordx4 v[168:169], v[182:185], off offset:528
	v_mul_f32_e32 v168, v171, v171
	v_mul_f32_e32 v169, v173, v173
	v_fmac_f32_e32 v174, v176, v176
	v_fmac_f32_e32 v168, v170, v170
	v_fmac_f32_e32 v169, v172, v172
	v_add_f32_e32 v174, v175, v174
	v_mul_f32_e32 v175, v179, v179
	v_add_f32_e32 v168, v168, v169
	v_mul_f32_e32 v169, v183, v183
	v_fmac_f32_e32 v175, v178, v178
	v_fmac_f32_e32 v169, v182, v182
	v_add_f32_e32 v174, v174, v175
	v_mul_f32_e32 v175, v181, v181
	v_add_f32_e32 v168, v168, v169
	v_mul_f32_e32 v169, v185, v185
	v_fmac_f32_e32 v175, v180, v180
	v_fmac_f32_e32 v169, v184, v184
	v_add_f32_e32 v178, v175, v174
	v_add_f32_e32 v168, v169, v168
	v_add_f32_e32 v168, v178, v168
	ds_bpermute_b32 v169, v197, v168
	v_cvt_pk_bf16_f32 v174, v170, v171
	v_cvt_pk_bf16_f32 v175, v172, v173
	v_cvt_pk_bf16_f32 v176, v182, v183
	v_cvt_pk_bf16_f32 v177, v184, v185
	s_waitcnt lgkmcnt(0)
	v_add_f32_e32 v168, v168, v169
	ds_bpermute_b32 v169, v196, v168
	buffer_store_dwordx4 v[174:177], v190, s[56:59], 0 offen offset:256 sc1
	s_and_saveexec_b64 s[2:3], s[40:41]
	s_cbranch_execz .LBB0_44
	s_waitcnt lgkmcnt(0)
	v_add_f32_e32 v170, v168, v169
	v_lshlrev_b64 v[168:169], 6, v[226:227]
	v_lshl_add_u64 v[168:169], s[66:67], 0, v[168:169]
	v_lshl_add_u64 v[168:169], s[44:45], 2, v[168:169]
	s_lshl_b32 s34, s51, 2
	v_lshl_add_u64 v[168:169], v[168:169], 0, s[34:35]
	global_store_dword v[168:169], v170, off sc1
; __device__ __forceinline__ unsigned cvt_pk_bf16(float lo, float hi) { f32x2_t v = {lo, hi}; bf16x2_t b = __builtin_convertvector(v, bf16x2_t); return __builtin_bit_cast(unsigned, b); }
; #define wt16(p, v) wt16b(WSB, (p), (v))
; __device__ __forceinline__ void wt4f(float* p, float v) { __hip_atomic_store(p, v, __ATOMIC_RELAXED, __HIP_MEMORY_SCOPE_AGENT); }
;     __device__ __forceinline__ void operator()(const f32x4 (&acc)[2][2][4][2], const pg8::Unit& u, int wr, int wc, int fr, int fq) const {
;     ...
;         for (int ai = 0; ai < 2; ++ai)
; #pragma unroll
;             for (int m = 0; m < 4; ++m) {
;                 const int row = row0 + ai * 128 + m * 16; float part = 0.f;
;                 f32x4 v[2][2];
; #pragma unroll
;                 for (int bj = 0; bj < 2; ++bj) { v[bj][0] = pre[m][bj][0] + acc[ai][bj][m][0] * scale; v[bj][1] = pre[m][bj][1] + acc[ai][bj][m][1] * scale; }
;                 if (ai == 0) {
; #pragma unroll
;                     for (int bj = 0; bj < 2; ++bj) { const size_t off2 = (size_t)(row + 128) * DM + col0 + bj * 128;
;                         pre[m][bj][0] = *(const f32x4*)(base + off2); pre[m][bj][1] = *(const f32x4*)(base + off2 + 4); }
;                 }
; #pragma unroll
;                 for (int bj = 0; bj < 2; ++bj) {
;                     const size_t off = (size_t)row * DM + col0 + bj * 128;
;                     const f32x4 v0 = v[bj][0], v1 = v[bj][1];
;                     *(f32x4*)(out + off) = v0; *(f32x4*)(out + off + 4) = v1;
;                     u32x4 w; w.x = cvt_pk_bf16(v0[0], v0[1]); w.y = cvt_pk_bf16(v0[2], v0[3]); w.z = cvt_pk_bf16(v1[0], v1[1]); w.w = cvt_pk_bf16(v1[2], v1[3]);
;                     wt16(xb + (size_t)row * XLD + col0 + bj * 128, w);
;                     part += (v0[0] * v0[0] + v0[1] * v0[1]) + (v0[2] * v0[2] + v0[3] * v0[3]) + (v1[0] * v1[0] + v1[1] * v1[1]) + (v1[2] * v1[2] + v1[3] * v1[3]);
;                 }
;                 part += __shfl_xor(part, 16); part += __shfl_xor(part, 32);
;                 if (fq == 0) wt4f(ss + (size_t)row * 16 + u.pn * 4 + wc, part);
.LBB0_44:
	s_or_b64 exec, exec, s[2:3]
	s_waitcnt vmcnt(24)
	s_nop 0
	v_pk_add_f32 v[172:173], v[82:83], v[146:147]
	v_add_u32_e32 v146, 0xa0, v214
	v_ashrrev_i32_e32 v147, 31, v146
	s_waitcnt lgkmcnt(0)
	v_pk_add_f32 v[168:169], v[90:91], v[150:151]
	v_lshlrev_b64 v[150:151], 12, v[146:147]
	v_lshl_add_u64 v[82:83], s[16:17], 0, v[150:151]
	v_pk_add_f32 v[174:175], v[84:85], v[148:149]
	v_lshl_add_u64 v[148:149], v[82:83], 0, v[212:213]
	v_pk_add_f32 v[160:161], v[96:97], v[160:161]
	v_pk_add_f32 v[158:159], v[94:95], v[158:159]
	v_pk_add_f32 v[170:171], v[92:93], v[152:153]
	v_pk_add_f32 v[156:157], v[88:89], v[156:157]
	v_pk_add_f32 v[154:155], v[86:87], v[154:155]
	global_load_dwordx4 v[86:89], v[148:149], off offset:16
	global_load_dwordx4 v[82:85], v[148:149], off
	global_load_dwordx4 v[94:97], v[148:149], off offset:528
	global_load_dwordx4 v[90:93], v[148:149], off offset:512
	v_lshl_add_u64 v[152:153], s[16:17], 0, v[224:225]
	v_lshl_add_u64 v[152:153], v[152:153], 0, v[212:213]
	global_store_dwordx4 v[152:153], v[158:161], off
	global_store_dwordx4 v[152:153], v[168:171], off offset:16
	v_cvt_pk_bf16_f32 v176, v158, v159
	v_mul_f32_e32 v159, v159, v159
	v_fmac_f32_e32 v159, v158, v158
	v_mul_f32_e32 v158, v161, v161
	v_fmac_f32_e32 v158, v160, v160
	v_add_f32_e32 v158, v159, v158
	v_mul_f32_e32 v159, v169, v169
	v_fmac_f32_e32 v159, v168, v168
	v_add_f32_e32 v158, v158, v159
	v_mul_f32_e32 v159, v171, v171
	v_add3_u32 v151, s5, v224, v167
	v_fmac_f32_e32 v159, v170, v170
	v_cvt_pk_bf16_f32 v177, v160, v161
	v_cvt_pk_bf16_f32 v178, v168, v169
	v_cvt_pk_bf16_f32 v179, v170, v171
	s_mov_b32 s58, s62
	s_mov_b32 s59, s63
	v_subrev_u32_e32 v151, s66, v151
	v_add_f32_e32 v168, v159, v158
	v_cvt_pk_bf16_f32 v158, v154, v155
	v_cvt_pk_bf16_f32 v159, v156, v157
	v_cvt_pk_bf16_f32 v160, v172, v173
	v_cvt_pk_bf16_f32 v161, v174, v175
	buffer_store_dwordx4 v[176:179], v151, s[56:59], 0 offen sc1
	global_store_dwordx4 v[152:153], v[154:157], off offset:512
	global_store_dwordx4 v[152:153], v[172:175], off offset:528
	buffer_store_dwordx4 v[158:161], v151, s[56:59], 0 offen offset:256 sc1
	v_mul_f32_e32 v151, v155, v155
	v_mul_f32_e32 v152, v157, v157
	v_fmac_f32_e32 v151, v154, v154
	v_fmac_f32_e32 v152, v156, v156
	v_add_f32_e32 v151, v151, v152
	v_mul_f32_e32 v152, v173, v173
	v_fmac_f32_e32 v152, v172, v172
	v_add_f32_e32 v151, v151, v152
	v_mul_f32_e32 v152, v175, v175
	v_fmac_f32_e32 v152, v174, v174
	v_add_f32_e32 v151, v152, v151
	v_add_f32_e32 v151, v168, v151
	ds_bpermute_b32 v152, v197, v151
	s_waitcnt lgkmcnt(0)
	v_add_f32_e32 v151, v151, v152
	ds_bpermute_b32 v152, v196, v151
	s_and_saveexec_b64 s[2:3], s[40:41]
	s_cbranch_execz .LBB0_46
	s_waitcnt lgkmcnt(0)
	v_add_f32_e32 v151, v151, v152
	v_lshlrev_b64 v[152:153], 6, v[222:223]
	v_lshl_add_u64 v[152:153], s[66:67], 0, v[152:153]
	v_lshl_add_u64 v[152:153], s[44:45], 2, v[152:153]
	s_lshl_b32 s34, s51, 2
	v_lshl_add_u64 v[152:153], v[152:153], 0, s[34:35]
	global_store_dword v[152:153], v151, off sc1
.LBB0_46:
	s_or_b64 exec, exec, s[2:3]
	s_waitcnt vmcnt(30)
	s_nop 0
	v_pk_add_f32 v[156:157], v[66:67], v[130:131]
	v_add_u32_e32 v130, 0xb0, v214
	v_ashrrev_i32_e32 v131, 31, v130
	s_waitcnt lgkmcnt(0)
	v_pk_add_f32 v[152:153], v[74:75], v[134:135]
	v_lshlrev_b64 v[134:135], 12, v[130:131]
	v_lshl_add_u64 v[66:67], s[16:17], 0, v[134:135]
	v_pk_add_f32 v[158:159], v[68:69], v[132:133]
	v_lshl_add_u64 v[132:133], v[66:67], 0, v[212:213]
	v_pk_add_f32 v[144:145], v[80:81], v[144:145]
	v_pk_add_f32 v[142:143], v[78:79], v[142:143]
	v_pk_add_f32 v[154:155], v[76:77], v[136:137]
	v_pk_add_f32 v[140:141], v[72:73], v[140:141]
	v_pk_add_f32 v[138:139], v[70:71], v[138:139]
	global_load_dwordx4 v[70:73], v[132:133], off offset:16
	global_load_dwordx4 v[66:69], v[132:133], off
	global_load_dwordx4 v[78:81], v[132:133], off offset:528
	global_load_dwordx4 v[74:77], v[132:133], off offset:512
	v_lshl_add_u64 v[136:137], s[16:17], 0, v[220:221]
	v_lshl_add_u64 v[136:137], v[136:137], 0, v[212:213]
	global_store_dwordx4 v[136:137], v[142:145], off
	global_store_dwordx4 v[136:137], v[152:155], off offset:16
	v_cvt_pk_bf16_f32 v168, v142, v143
	v_mul_f32_e32 v143, v143, v143
	v_fmac_f32_e32 v143, v142, v142
	v_mul_f32_e32 v142, v145, v145
	v_fmac_f32_e32 v142, v144, v144
	v_add_f32_e32 v142, v143, v142
	v_mul_f32_e32 v143, v153, v153
	v_fmac_f32_e32 v143, v152, v152
	v_add_f32_e32 v142, v142, v143
	v_mul_f32_e32 v143, v155, v155
	v_add3_u32 v135, s5, v220, v167
	v_fmac_f32_e32 v143, v154, v154
	v_cvt_pk_bf16_f32 v169, v144, v145
	v_cvt_pk_bf16_f32 v170, v152, v153
	v_cvt_pk_bf16_f32 v171, v154, v155
	v_subrev_u32_e32 v135, s66, v135
	v_add_f32_e32 v151, v143, v142
	v_cvt_pk_bf16_f32 v142, v138, v139
	v_cvt_pk_bf16_f32 v143, v140, v141
	v_cvt_pk_bf16_f32 v144, v156, v157
	v_cvt_pk_bf16_f32 v145, v158, v159
	buffer_store_dwordx4 v[168:171], v135, s[56:59], 0 offen sc1
	global_store_dwordx4 v[136:137], v[138:141], off offset:512
	global_store_dwordx4 v[136:137], v[156:159], off offset:528
	buffer_store_dwordx4 v[142:145], v135, s[56:59], 0 offen offset:256 sc1
	v_mul_f32_e32 v135, v139, v139
	v_mul_f32_e32 v136, v141, v141
	v_fmac_f32_e32 v135, v138, v138
	v_fmac_f32_e32 v136, v140, v140
	v_add_f32_e32 v135, v135, v136
	v_mul_f32_e32 v136, v157, v157
	v_fmac_f32_e32 v136, v156, v156
	v_add_f32_e32 v135, v135, v136
	v_mul_f32_e32 v136, v159, v159
	v_fmac_f32_e32 v136, v158, v158
	v_add_f32_e32 v135, v136, v135
	v_add_f32_e32 v135, v151, v135
	ds_bpermute_b32 v136, v197, v135
	s_waitcnt lgkmcnt(0)
	v_add_f32_e32 v135, v135, v136
	ds_bpermute_b32 v136, v196, v135
	s_and_saveexec_b64 s[2:3], s[40:41]
	s_cbranch_execz .LBB0_48
	s_waitcnt lgkmcnt(0)
	v_add_f32_e32 v135, v135, v136
	v_lshlrev_b64 v[136:137], 6, v[208:209]
	v_lshl_add_u64 v[136:137], s[66:67], 0, v[136:137]
	v_lshl_add_u64 v[136:137], s[44:45], 2, v[136:137]
	s_lshl_b32 s34, s51, 2
	v_lshl_add_u64 v[136:137], v[136:137], 0, s[34:35]
	global_store_dword v[136:137], v135, off sc1

; __device__ __forceinline__ unsigned cvt_pk_bf16(float lo, float hi) { f32x2_t v = {lo, hi}; bf16x2_t b = __builtin_convertvector(v, bf16x2_t); return __builtin_bit_cast(unsigned, b); }
; #define wt16(p, v) wt16b(WSB, (p), (v))
;     __device__ __forceinline__ void operator()(const f32x4 (&acc)[2][2][4][2], const pg8::Unit& u, int wr, int wc, int fr, int fq) const {
;         const int row0 = u.pm * 256 + wr * 64 + fr, col0 = u.pn * 256 + wc * 32 + 8 * fq;
;         f32x4 pre[4][2][2];
; #pragma unroll
;         for (int m = 0; m < 4; ++m)
; #pragma unroll
;             for (int bj = 0; bj < 2; ++bj) { const size_t off = (size_t)(row0 + m * 16) * DM + col0 + bj * 128;
;                 pre[m][bj][0] = *(const f32x4*)(base + off); pre[m][bj][1] = *(const f32x4*)(base + off + 4); }
; #pragma unroll
;         for (int ai = 0; ai < 2; ++ai)
; #pragma unroll
;             for (int m = 0; m < 4; ++m) {
;                 const int row = row0 + ai * 128 + m * 16; float part = 0.f;
;                 f32x4 v[2][2];
; #pragma unroll
;                 for (int bj = 0; bj < 2; ++bj) { v[bj][0] = pre[m][bj][0] + acc[ai][bj][m][0] * scale; v[bj][1] = pre[m][bj][1] + acc[ai][bj][m][1] * scale; }
;                 if (ai == 0) {
; #pragma unroll
;                     for (int bj = 0; bj < 2; ++bj) { const size_t off2 = (size_t)(row + 128) * DM + col0 + bj * 128;
;                         pre[m][bj][0] = *(const f32x4*)(base + off2); pre[m][bj][1] = *(const f32x4*)(base + off2 + 4); }
;                 }
; #pragma unroll
;                 for (int bj = 0; bj < 2; ++bj) {
;                     const size_t off = (size_t)row * DM + col0 + bj * 128;
;                     const f32x4 v0 = v[bj][0], v1 = v[bj][1];
;                     *(f32x4*)(out + off) = v0; *(f32x4*)(out + off + 4) = v1;
;                     u32x4 w; w.x = cvt_pk_bf16(v0[0], v0[1]); w.y = cvt_pk_bf16(v0[2], v0[3]); w.z = cvt_pk_bf16(v1[0], v1[1]); w.w = cvt_pk_bf16(v1[2], v1[3]);
;                     wt16(xb + (size_t)row * XLD + col0 + bj * 128, w);
;                     part += (v0[0] * v0[0] + v0[1] * v0[1]) + (v0[2] * v0[2] + v0[3] * v0[3]) + (v1[0] * v1[0] + v1[1] * v1[1]) + (v1[2] * v1[2] + v1[3] * v1[3]);
;                 }
;                 part += __shfl_xor(part, 16); part += __shfl_xor(part, 32);
;                 if (fq == 0) wt4f(ss + (size_t)row * 16 + u.pn * 4 + wc, part);
.LBB0_336:
	v_lshl_or_b32 v156, s48, 8, v194
	v_lshl_add_u32 v202, s50, 8, v246
	v_ashrrev_i32_e32 v157, 31, v156
	v_lshlrev_b64 v[198:199], 2, v[156:157]
	v_ashrrev_i32_e32 v203, 31, v202
	v_lshl_add_u64 v[18:19], s[14:15], 0, v[198:199]
	v_lshlrev_b64 v[242:243], 12, v[202:203]
	v_lshl_add_u64 v[14:15], v[18:19], 0, v[242:243]
	global_load_dwordx4 v[2:5], v[14:15], off offset:16
	global_load_dwordx4 v[6:9], v[14:15], off
	global_load_dwordx4 v[10:13], v[14:15], off offset:528
	s_nop 0
	global_load_dwordx4 v[14:17], v[14:15], off offset:512
	v_and_b32_e32 v67, 64, v247
	v_xor_b32_e32 v66, 16, v247
	v_add_u32_e32 v67, 64, v67
	v_cmp_lt_i32_e32 vcc, v66, v67
	v_or_b32_e32 v226, 16, v202
	v_ashrrev_i32_e32 v227, 31, v226
	v_cndmask_b32_e32 v66, v247, v66, vcc
	v_or_b32_e32 v222, 32, v202
	v_or_b32_e32 v190, 48, v202
	v_lshlrev_b32_e32 v197, 2, v66
	v_xor_b32_e32 v66, 32, v247
	v_lshlrev_b64 v[228:229], 12, v[226:227]
	v_ashrrev_i32_e32 v223, 31, v222
	v_ashrrev_i32_e32 v191, 31, v190
	v_cmp_lt_i32_e32 vcc, v66, v67
	v_lshl_add_u64 v[20:21], v[18:19], 0, v[228:229]
	v_lshlrev_b64 v[224:225], 12, v[222:223]
	v_lshlrev_b64 v[220:221], 12, v[190:191]
	v_cndmask_b32_e32 v66, v247, v66, vcc
	global_load_dwordx4 v[54:57], v[20:21], off offset:16
	global_load_dwordx4 v[62:65], v[20:21], off
	global_load_dwordx4 v[50:53], v[20:21], off offset:528
	global_load_dwordx4 v[58:61], v[20:21], off offset:512
	v_lshl_add_u64 v[20:21], v[18:19], 0, v[224:225]
	v_lshl_add_u64 v[26:27], v[18:19], 0, v[220:221]
	v_lshlrev_b32_e32 v196, 2, v66
	global_load_dwordx4 v[38:41], v[20:21], off offset:16
	global_load_dwordx4 v[46:49], v[20:21], off
	global_load_dwordx4 v[34:37], v[20:21], off offset:528
	global_load_dwordx4 v[42:45], v[20:21], off offset:512
	global_load_dwordx4 v[22:25], v[26:27], off offset:16
	global_load_dwordx4 v[30:33], v[26:27], off
	s_nop 0
	global_load_dwordx4 v[18:21], v[26:27], off offset:528
	s_nop 0
	global_load_dwordx4 v[26:29], v[26:27], off offset:512
	s_mov_b32 s58, s62
	s_mov_b32 s59, s63
	s_lshl_b32 s44, s48, 2
	s_ashr_i32 s45, s44, 31
	s_waitcnt vmcnt(12)
	v_pk_add_f32 v[74:75], v[232:233], v[2:3]
	v_pk_add_f32 v[80:81], v[8:9], v[192:193]
	v_add_u32_e32 v192, 0x80, v202
	v_ashrrev_i32_e32 v193, 31, v192
	v_pk_add_f32 v[78:79], v[6:7], v[214:215]
	v_lshlrev_b64 v[214:215], 12, v[192:193]
	v_lshl_add_u64 v[2:3], s[14:15], 0, v[214:215]
	v_pk_add_f32 v[66:67], v[240:241], v[10:11]
	v_lshl_add_u64 v[10:11], v[2:3], 0, v[198:199]
	v_pk_add_f32 v[76:77], v[230:231], v[4:5]
	v_pk_add_f32 v[72:73], v[234:235], v[16:17]
	v_pk_add_f32 v[70:71], v[236:237], v[14:15]
	v_pk_add_f32 v[68:69], v[238:239], v[12:13]
	global_load_dwordx4 v[6:9], v[10:11], off offset:16
	global_load_dwordx4 v[2:5], v[10:11], off
	global_load_dwordx4 v[14:17], v[10:11], off offset:528
	s_nop 0
	global_load_dwordx4 v[10:13], v[10:11], off offset:512
	s_waitcnt lgkmcnt(0)
	v_lshl_add_u64 v[230:231], s[16:17], 0, v[242:243]
	v_lshl_add_u64 v[234:235], v[230:231], 0, v[198:199]
	global_store_dwordx4 v[234:235], v[78:81], off
	global_store_dwordx4 v[234:235], v[74:77], off offset:16
	v_cvt_pk_bf16_f32 v230, v78, v79
	v_mul_f32_e32 v79, v79, v79
	v_fmac_f32_e32 v79, v78, v78
	v_mul_f32_e32 v78, v81, v81
	v_cvt_pk_bf16_f32 v232, v74, v75
	v_fmac_f32_e32 v78, v80, v80
	v_mul_f32_e32 v75, v75, v75
	v_lshlrev_b32_e32 v236, 1, v156
	v_add_f32_e32 v78, v79, v78
	v_fmac_f32_e32 v75, v74, v74
	v_add3_u32 v236, s5, v242, v236
	v_add_f32_e32 v74, v78, v75
	v_mul_f32_e32 v75, v77, v77
	v_cvt_pk_bf16_f32 v231, v80, v81
	v_cvt_pk_bf16_f32 v233, v76, v77
	v_subrev_u32_e32 v236, s66, v236
	v_fmac_f32_e32 v75, v76, v76
	buffer_store_dwordx4 v[230:233], v236, s[56:59], 0 offen sc1
	v_add_f32_e32 v78, v75, v74
	global_store_dwordx4 v[234:235], v[70:73], off offset:512
	global_store_dwordx4 v[234:235], v[66:69], off offset:528
	v_cvt_pk_bf16_f32 v74, v70, v71
	v_mul_f32_e32 v71, v71, v71
	v_fmac_f32_e32 v71, v70, v70
	v_mul_f32_e32 v70, v73, v73
	v_cvt_pk_bf16_f32 v76, v66, v67
	v_fmac_f32_e32 v70, v72, v72
	v_mul_f32_e32 v67, v67, v67
	v_add_f32_e32 v70, v71, v70
	v_fmac_f32_e32 v67, v66, v66
	v_add_f32_e32 v66, v70, v67
	v_mul_f32_e32 v67, v69, v69
	v_fmac_f32_e32 v67, v68, v68
	v_add_f32_e32 v66, v67, v66
	v_add_f32_e32 v66, v78, v66
	ds_bpermute_b32 v67, v197, v66
	v_cvt_pk_bf16_f32 v75, v72, v73
	v_cvt_pk_bf16_f32 v77, v68, v69
	buffer_store_dwordx4 v[74:77], v236, s[56:59], 0 offen offset:256 sc1
	s_waitcnt lgkmcnt(0)
	v_add_f32_e32 v66, v66, v67
	ds_bpermute_b32 v67, v196, v66
	s_and_saveexec_b64 s[2:3], s[40:41]
	s_cbranch_execz .LBB0_338
	s_waitcnt lgkmcnt(0)
	v_add_f32_e32 v68, v66, v67
	v_lshlrev_b64 v[66:67], 6, v[202:203]
	v_lshl_add_u64 v[66:67], s[66:67], 0, v[66:67]
	v_lshl_add_u64 v[66:67], s[44:45], 2, v[66:67]
	s_lshl_b32 s34, s55, 2
	v_lshl_add_u64 v[66:67], v[66:67], 0, s[34:35]
	global_store_dword v[66:67], v68, off sc1
; __device__ __forceinline__ unsigned cvt_pk_bf16(float lo, float hi) { f32x2_t v = {lo, hi}; bf16x2_t b = __builtin_convertvector(v, bf16x2_t); return __builtin_bit_cast(unsigned, b); }
; #define wt16(p, v) wt16b(WSB, (p), (v))
; __device__ __forceinline__ void wt4f(float* p, float v) { __hip_atomic_store(p, v, __ATOMIC_RELAXED, __HIP_MEMORY_SCOPE_AGENT); }
;     __device__ __forceinline__ void operator()(const f32x4 (&acc)[2][2][4][2], const pg8::Unit& u, int wr, int wc, int fr, int fq) const {
;     ...
;         for (int ai = 0; ai < 2; ++ai)
; #pragma unroll
;             for (int m = 0; m < 4; ++m) {
;                 const int row = row0 + ai * 128 + m * 16; float part = 0.f;
;                 f32x4 v[2][2];
; #pragma unroll
;                 for (int bj = 0; bj < 2; ++bj) { v[bj][0] = pre[m][bj][0] + acc[ai][bj][m][0] * scale; v[bj][1] = pre[m][bj][1] + acc[ai][bj][m][1] * scale; }
;                 if (ai == 0) {
; #pragma unroll
;                     for (int bj = 0; bj < 2; ++bj) { const size_t off2 = (size_t)(row + 128) * DM + col0 + bj * 128;
;                         pre[m][bj][0] = *(const f32x4*)(base + off2); pre[m][bj][1] = *(const f32x4*)(base + off2 + 4); }
;                 }
; #pragma unroll
;                 for (int bj = 0; bj < 2; ++bj) {
;                     const size_t off = (size_t)row * DM + col0 + bj * 128;
;                     const f32x4 v0 = v[bj][0], v1 = v[bj][1];
;                     *(f32x4*)(out + off) = v0; *(f32x4*)(out + off + 4) = v1;
;                     u32x4 w; w.x = cvt_pk_bf16(v0[0], v0[1]); w.y = cvt_pk_bf16(v0[2], v0[3]); w.z = cvt_pk_bf16(v1[0], v1[1]); w.w = cvt_pk_bf16(v1[2], v1[3]);
;                     wt16(xb + (size_t)row * XLD + col0 + bj * 128, w);
;                     part += (v0[0] * v0[0] + v0[1] * v0[1]) + (v0[2] * v0[2] + v0[3] * v0[3]) + (v1[0] * v1[0] + v1[1] * v1[1]) + (v1[2] * v1[2] + v1[3] * v1[3]);
;                 }
;                 part += __shfl_xor(part, 16); part += __shfl_xor(part, 32);
;                 if (fq == 0) wt4f(ss + (size_t)row * 16 + u.pn * 4 + wc, part);
.LBB0_338:
	s_or_b64 exec, exec, s[2:3]
	v_add_u32_e32 v66, 0x90, v202
	s_waitcnt lgkmcnt(0)
	v_ashrrev_i32_e32 v67, 31, v66
	v_lshlrev_b64 v[68:69], 12, v[66:67]
	s_waitcnt vmcnt(18)
	s_nop 0
	v_pk_add_f32 v[74:75], v[208:209], v[54:55]
	v_pk_add_f32 v[208:209], v[218:219], v[50:51]
	v_lshl_add_u64 v[50:51], s[14:15], 0, v[68:69]
	v_pk_add_f32 v[70:71], v[204:205], v[62:63]
	v_pk_add_f32 v[204:205], v[212:213], v[58:59]
	v_lshl_add_u64 v[58:59], v[50:51], 0, v[198:199]
	v_pk_add_f32 v[72:73], v[200:201], v[64:65]
	v_pk_add_f32 v[76:77], v[206:207], v[56:57]
	v_pk_add_f32 v[206:207], v[210:211], v[60:61]
	v_pk_add_f32 v[210:211], v[216:217], v[52:53]
	global_load_dwordx4 v[54:57], v[58:59], off offset:16
	global_load_dwordx4 v[50:53], v[58:59], off
	global_load_dwordx4 v[62:65], v[58:59], off offset:528
	s_nop 0
	global_load_dwordx4 v[58:61], v[58:59], off offset:512
	v_lshl_add_u64 v[78:79], s[16:17], 0, v[228:229]
	v_lshl_add_u64 v[80:81], v[78:79], 0, v[198:199]
	global_store_dwordx4 v[80:81], v[70:73], off
	global_store_dwordx4 v[80:81], v[74:77], off offset:16
	v_cvt_pk_bf16_f32 v216, v70, v71
	v_mul_f32_e32 v71, v71, v71
	v_fmac_f32_e32 v71, v70, v70
	v_mul_f32_e32 v70, v73, v73
	v_fmac_f32_e32 v70, v72, v72
	v_add_f32_e32 v70, v71, v70
	v_mul_f32_e32 v71, v75, v75
	v_fmac_f32_e32 v71, v74, v74
	v_lshlrev_b32_e32 v78, 1, v156
	v_add_f32_e32 v70, v70, v71
	v_mul_f32_e32 v71, v77, v77
	v_add3_u32 v79, s5, v228, v78
	v_fmac_f32_e32 v71, v76, v76
	v_cvt_pk_bf16_f32 v217, v72, v73
	v_cvt_pk_bf16_f32 v218, v74, v75
	v_cvt_pk_bf16_f32 v219, v76, v77
	v_subrev_u32_e32 v79, s66, v79
	v_add_f32_e32 v74, v71, v70
	v_cvt_pk_bf16_f32 v70, v204, v205
	v_cvt_pk_bf16_f32 v71, v206, v207
	v_cvt_pk_bf16_f32 v72, v208, v209
	v_cvt_pk_bf16_f32 v73, v210, v211
	buffer_store_dwordx4 v[216:219], v79, s[56:59], 0 offen sc1
	global_store_dwordx4 v[80:81], v[204:207], off offset:512
	global_store_dwordx4 v[80:81], v[208:211], off offset:528
	buffer_store_dwordx4 v[70:73], v79, s[56:59], 0 offen offset:256 sc1
	s_nop 1
	v_mul_f32_e32 v70, v205, v205
	v_mul_f32_e32 v71, v207, v207
	v_fmac_f32_e32 v70, v204, v204
	v_fmac_f32_e32 v71, v206, v206
	v_add_f32_e32 v70, v70, v71
	v_mul_f32_e32 v71, v209, v209
	v_fmac_f32_e32 v71, v208, v208
	v_add_f32_e32 v70, v70, v71
	v_mul_f32_e32 v71, v211, v211
	v_fmac_f32_e32 v71, v210, v210
	v_add_f32_e32 v70, v71, v70
	v_add_f32_e32 v70, v74, v70
	ds_bpermute_b32 v71, v197, v70
	s_waitcnt lgkmcnt(0)
	v_add_f32_e32 v70, v70, v71
	ds_bpermute_b32 v71, v196, v70
	s_and_saveexec_b64 s[2:3], s[40:41]
	s_cbranch_execz .LBB0_340
	s_waitcnt lgkmcnt(0)
	v_add_f32_e32 v72, v70, v71
	v_lshlrev_b64 v[70:71], 6, v[226:227]
	v_lshl_add_u64 v[70:71], s[66:67], 0, v[70:71]
	v_lshl_add_u64 v[70:71], s[44:45], 2, v[70:71]
	s_lshl_b32 s34, s55, 2
	v_lshl_add_u64 v[70:71], v[70:71], 0, s[34:35]
	global_store_dword v[70:71], v72, off sc1
.LBB0_340:
	s_or_b64 exec, exec, s[2:3]
	v_add_u32_e32 v70, 0xa0, v202
	s_waitcnt lgkmcnt(0)
	v_ashrrev_i32_e32 v71, 31, v70
	v_lshlrev_b64 v[72:73], 12, v[70:71]
	s_waitcnt vmcnt(24)
	s_nop 0
	v_pk_add_f32 v[76:77], v[174:175], v[48:49]
	v_pk_add_f32 v[174:175], v[180:181], v[38:39]
	v_pk_add_f32 v[180:181], v[182:183], v[44:45]
	v_pk_add_f32 v[182:183], v[188:189], v[34:35]
	v_lshl_add_u64 v[34:35], s[14:15], 0, v[72:73]
	v_pk_add_f32 v[74:75], v[176:177], v[46:47]
	v_pk_add_f32 v[176:177], v[178:179], v[40:41]
	v_pk_add_f32 v[178:179], v[184:185], v[42:43]
	v_lshl_add_u64 v[42:43], v[34:35], 0, v[198:199]
	v_pk_add_f32 v[184:185], v[186:187], v[36:37]
	global_load_dwordx4 v[38:41], v[42:43], off offset:16
	global_load_dwordx4 v[34:37], v[42:43], off
	global_load_dwordx4 v[46:49], v[42:43], off offset:528
	s_nop 0
	global_load_dwordx4 v[42:45], v[42:43], off offset:512
	v_lshl_add_u64 v[80:81], s[16:17], 0, v[224:225]
	v_lshl_add_u64 v[80:81], v[80:81], 0, v[198:199]
	global_store_dwordx4 v[80:81], v[74:77], off
	global_store_dwordx4 v[80:81], v[174:177], off offset:16
	v_cvt_pk_bf16_f32 v186, v74, v75
	v_mul_f32_e32 v75, v75, v75
	v_fmac_f32_e32 v75, v74, v74
	v_mul_f32_e32 v74, v77, v77
	v_fmac_f32_e32 v74, v76, v76
	v_add_f32_e32 v74, v75, v74
	v_mul_f32_e32 v75, v175, v175
	v_fmac_f32_e32 v75, v174, v174
	v_add_f32_e32 v74, v74, v75
	v_mul_f32_e32 v75, v177, v177
	v_add3_u32 v79, s5, v224, v78
	v_fmac_f32_e32 v75, v176, v176
	v_cvt_pk_bf16_f32 v187, v76, v77
	v_cvt_pk_bf16_f32 v188, v174, v175
	v_cvt_pk_bf16_f32 v189, v176, v177
	s_mov_b32 s58, s62
	s_mov_b32 s59, s63
	v_subrev_u32_e32 v79, s66, v79
	v_add_f32_e32 v174, v75, v74
	v_cvt_pk_bf16_f32 v74, v178, v179
	v_cvt_pk_bf16_f32 v75, v180, v181
	v_cvt_pk_bf16_f32 v76, v182, v183
	v_cvt_pk_bf16_f32 v77, v184, v185
	buffer_store_dwordx4 v[186:189], v79, s[56:59], 0 offen sc1
	global_store_dwordx4 v[80:81], v[178:181], off offset:512
	global_store_dwordx4 v[80:81], v[182:185], off offset:528
	buffer_store_dwordx4 v[74:77], v79, s[56:59], 0 offen offset:256 sc1
	s_nop 1
	v_mul_f32_e32 v74, v179, v179
	v_mul_f32_e32 v75, v181, v181
	v_fmac_f32_e32 v74, v178, v178
	v_fmac_f32_e32 v75, v180, v180
	v_add_f32_e32 v74, v74, v75
	v_mul_f32_e32 v75, v183, v183
	v_fmac_f32_e32 v75, v182, v182
	v_add_f32_e32 v74, v74, v75
	v_mul_f32_e32 v75, v185, v185
	v_fmac_f32_e32 v75, v184, v184
	v_add_f32_e32 v74, v75, v74
	v_add_f32_e32 v74, v174, v74
	ds_bpermute_b32 v75, v197, v74
	s_waitcnt lgkmcnt(0)
	v_add_f32_e32 v74, v74, v75
	ds_bpermute_b32 v75, v196, v74
	s_and_saveexec_b64 s[2:3], s[40:41]
	s_cbranch_execz .LBB0_342
	s_waitcnt lgkmcnt(0)
	v_add_f32_e32 v76, v74, v75
	v_lshlrev_b64 v[74:75], 6, v[222:223]
	v_lshl_add_u64 v[74:75], s[66:67], 0, v[74:75]
	v_lshl_add_u64 v[74:75], s[44:45], 2, v[74:75]
	s_lshl_b32 s34, s55, 2
	v_lshl_add_u64 v[74:75], v[74:75], 0, s[34:35]
	global_store_dword v[74:75], v76, off sc1
; __device__ __forceinline__ unsigned cvt_pk_bf16(float lo, float hi) { f32x2_t v = {lo, hi}; bf16x2_t b = __builtin_convertvector(v, bf16x2_t); return __builtin_bit_cast(unsigned, b); }
; #define wt16(p, v) wt16b(WSB, (p), (v))
; __device__ __forceinline__ void wt4f(float* p, float v) { __hip_atomic_store(p, v, __ATOMIC_RELAXED, __HIP_MEMORY_SCOPE_AGENT); }
;     __device__ __forceinline__ void operator()(const f32x4 (&acc)[2][2][4][2], const pg8::Unit& u, int wr, int wc, int fr, int fq) const {
;     ...
;         for (int ai = 0; ai < 2; ++ai)
; #pragma unroll
;             for (int m = 0; m < 4; ++m) {
;                 const int row = row0 + ai * 128 + m * 16; float part = 0.f;
;                 f32x4 v[2][2];
; #pragma unroll
;                 for (int bj = 0; bj < 2; ++bj) { v[bj][0] = pre[m][bj][0] + acc[ai][bj][m][0] * scale; v[bj][1] = pre[m][bj][1] + acc[ai][bj][m][1] * scale; }
;                 if (ai == 0) {
; #pragma unroll
;                     for (int bj = 0; bj < 2; ++bj) { const size_t off2 = (size_t)(row + 128) * DM + col0 + bj * 128;
;                         pre[m][bj][0] = *(const f32x4*)(base + off2); pre[m][bj][1] = *(const f32x4*)(base + off2 + 4); }
;                 }
; #pragma unroll
;                 for (int bj = 0; bj < 2; ++bj) {
;                     const size_t off = (size_t)row * DM + col0 + bj * 128;
;                     const f32x4 v0 = v[bj][0], v1 = v[bj][1];
;                     *(f32x4*)(out + off) = v0; *(f32x4*)(out + off + 4) = v1;
;                     u32x4 w; w.x = cvt_pk_bf16(v0[0], v0[1]); w.y = cvt_pk_bf16(v0[2], v0[3]); w.z = cvt_pk_bf16(v1[0], v1[1]); w.w = cvt_pk_bf16(v1[2], v1[3]);
;                     wt16(xb + (size_t)row * XLD + col0 + bj * 128, w);
;                     part += (v0[0] * v0[0] + v0[1] * v0[1]) + (v0[2] * v0[2] + v0[3] * v0[3]) + (v1[0] * v1[0] + v1[1] * v1[1]) + (v1[2] * v1[2] + v1[3] * v1[3]);
;                 }
;                 part += __shfl_xor(part, 16); part += __shfl_xor(part, 32);
;                 if (fq == 0) wt4f(ss + (size_t)row * 16 + u.pn * 4 + wc, part);
.LBB0_342:
	s_or_b64 exec, exec, s[2:3]
	v_add_u32_e32 v74, 0xb0, v202
	s_waitcnt lgkmcnt(0)
	v_ashrrev_i32_e32 v75, 31, v74
	v_lshlrev_b64 v[76:77], 12, v[74:75]
	s_waitcnt vmcnt(30)
	s_nop 0
	v_pk_add_f32 v[176:177], v[158:159], v[32:33]
	v_pk_add_f32 v[158:159], v[164:165], v[22:23]
	v_pk_add_f32 v[164:165], v[166:167], v[28:29]
	v_pk_add_f32 v[166:167], v[172:173], v[18:19]
	v_lshl_add_u64 v[18:19], s[14:15], 0, v[76:77]
	v_pk_add_f32 v[174:175], v[160:161], v[30:31]
	v_pk_add_f32 v[160:161], v[162:163], v[24:25]
	v_pk_add_f32 v[162:163], v[168:169], v[26:27]
	v_lshl_add_u64 v[26:27], v[18:19], 0, v[198:199]
	v_pk_add_f32 v[168:169], v[170:171], v[20:21]
	global_load_dwordx4 v[22:25], v[26:27], off offset:16
	global_load_dwordx4 v[18:21], v[26:27], off
	global_load_dwordx4 v[30:33], v[26:27], off offset:528
	s_nop 0
	global_load_dwordx4 v[26:29], v[26:27], off offset:512
	v_lshl_add_u64 v[80:81], s[16:17], 0, v[220:221]
	v_add3_u32 v79, s5, v220, v78
	v_lshl_add_u64 v[80:81], v[80:81], 0, v[198:199]
	v_cvt_pk_bf16_f32 v170, v174, v175
	v_cvt_pk_bf16_f32 v171, v176, v177
	v_cvt_pk_bf16_f32 v172, v158, v159
	v_cvt_pk_bf16_f32 v173, v160, v161
	v_subrev_u32_e32 v79, s66, v79
	global_store_dwordx4 v[80:81], v[174:177], off
	global_store_dwordx4 v[80:81], v[158:161], off offset:16
	buffer_store_dwordx4 v[170:173], v79, s[56:59], 0 offen sc1
	global_store_dwordx4 v[80:81], v[162:165], off offset:512
	global_store_dwordx4 v[80:81], v[166:169], off offset:528
	v_mul_f32_e32 v170, v175, v175
	v_mul_f32_e32 v171, v177, v177
	v_fmac_f32_e32 v170, v174, v174
	v_fmac_f32_e32 v171, v176, v176
	v_mul_f32_e32 v159, v159, v159
	v_add_f32_e32 v170, v170, v171
	v_fmac_f32_e32 v159, v158, v158
	v_add_f32_e32 v158, v170, v159
	v_mul_f32_e32 v159, v161, v161
	v_fmac_f32_e32 v159, v160, v160
	v_add_f32_e32 v170, v159, v158
	v_cvt_pk_bf16_f32 v158, v162, v163
	v_cvt_pk_bf16_f32 v159, v164, v165
	v_cvt_pk_bf16_f32 v160, v166, v167
	v_cvt_pk_bf16_f32 v161, v168, v169
	buffer_store_dwordx4 v[158:161], v79, s[56:59], 0 offen offset:256 sc1
	v_mul_f32_e32 v79, v163, v163
	v_mul_f32_e32 v80, v165, v165
	v_fmac_f32_e32 v79, v162, v162
	v_fmac_f32_e32 v80, v164, v164
	v_add_f32_e32 v79, v79, v80
	v_mul_f32_e32 v80, v167, v167
	v_fmac_f32_e32 v80, v166, v166
	v_add_f32_e32 v79, v79, v80
	v_mul_f32_e32 v80, v169, v169
	v_fmac_f32_e32 v80, v168, v168
	v_add_f32_e32 v79, v80, v79
	v_add_f32_e32 v79, v170, v79
	ds_bpermute_b32 v80, v197, v79
	s_waitcnt lgkmcnt(0)
	v_add_f32_e32 v79, v79, v80
	ds_bpermute_b32 v80, v196, v79
	s_and_saveexec_b64 s[2:3], s[40:41]
	s_cbranch_execz .LBB0_344
	s_waitcnt lgkmcnt(0)
	v_add_f32_e32 v79, v79, v80
	v_lshlrev_b64 v[80:81], 6, v[190:191]
	v_lshl_add_u64 v[80:81], s[66:67], 0, v[80:81]
	v_lshl_add_u64 v[80:81], s[44:45], 2, v[80:81]
	s_lshl_b32 s34, s55, 2
	v_lshl_add_u64 v[80:81], v[80:81], 0, s[34:35]
	global_store_dword v[80:81], v79, off sc1
